# grid barrier: non-leader workgroups issue the L1 invalidate (buffer_inv sc1) before polling the release word instead of after
# baseline (speedup 1.0000x reference)
.LBB0_88:
	s_lshl_b32 s1, s0, 8
	s_add_u32 s6, s48, s1
	s_addc_u32 s7, s49, 0
	v_mov_b32_e32 v1, 0x1000
	v_mov_b32_e32 v3, 1
	global_atomic_add v3, v1, v3, s[6:7] offset:1024 sc0
	v_cvt_f32_u32_e32 v1, v2
	v_sub_u32_e32 v4, 0, v2
	v_rcp_iflag_f32_e32 v1, v1
	s_nop 0
	v_mul_f32_e32 v1, 0x4f7ffffe, v1
	v_cvt_u32_f32_e32 v1, v1
	v_mul_lo_u32 v4, v4, v1
	v_mul_hi_u32 v4, v1, v4
	v_add_u32_e32 v1, v1, v4
	s_waitcnt vmcnt(0)
	v_mul_hi_u32 v1, v3, v1
	v_mul_lo_u32 v4, v1, v2
	v_sub_u32_e32 v4, v3, v4
	v_add_u32_e32 v5, 1, v1
	v_cmp_ge_u32_e32 vcc, v4, v2
	v_add_u32_e32 v3, 1, v3
	s_nop 0
	v_cndmask_b32_e32 v1, v1, v5, vcc
	v_sub_u32_e32 v5, v4, v2
	v_cndmask_b32_e32 v4, v4, v5, vcc
	v_add_u32_e32 v5, 1, v1
	v_cmp_ge_u32_e32 vcc, v4, v2
	s_nop 1
	v_cndmask_b32_e32 v1, v1, v5, vcc
	v_mul_lo_u32 v4, v2, v1
	v_add_u32_e32 v2, v4, v2
	v_cmp_ne_u32_e32 vcc, v3, v2
	s_and_saveexec_b64 s[8:9], vcc
	s_xor_b64 s[8:9], exec, s[8:9]
	s_cbranch_execz .LBB0_102
	buffer_inv sc1
	s_waitcnt lgkmcnt(0)
	v_mov_b32_e32 v0, 0x2000
	global_load_dword v0, v0, s[6:7] offset:1024 sc1
	s_add_u32 s14, s6, 0x2400
	s_addc_u32 s15, s7, 0
	s_waitcnt vmcnt(0)
	v_cmp_eq_u32_e32 vcc, v0, v1
	s_and_saveexec_b64 s[10:11], vcc
	s_cbranch_execz .LBB0_101
	v_readlane_b32 s12, v251, 7
	v_readlane_b32 s13, v251, 8
	s_load_dwordx2 s[12:13], s[12:13], 0xc8
	s_mov_b32 s1, 1
	s_mov_b64 s[16:17], 0
	v_mov_b32_e32 v0, 0
	s_waitcnt lgkmcnt(0)
	s_add_u32 s12, s12, 0x16900200
	s_addc_u32 s13, s13, 0
	s_branch .LBB0_92

.LBB0_101:
	s_or_b64 exec, exec, s[10:11]
	s_waitcnt vmcnt(0)
	s_waitcnt vmcnt(0)

.LBB0_585:
	v_readlane_b32 s2, v252, 47
	v_readlane_b32 s3, v252, 48
	v_cvt_f32_u32_e32 v1, v2
	v_sub_u32_e32 v4, 0, v2
	v_rcp_iflag_f32_e32 v1, v1
	s_nop 1
	global_atomic_add v3, v197, v223, s[2:3] sc0
	v_mul_f32_e32 v1, 0x4f7ffffe, v1
	v_cvt_u32_f32_e32 v1, v1
	v_mul_lo_u32 v4, v4, v1
	v_mul_hi_u32 v4, v1, v4
	v_add_u32_e32 v1, v1, v4
	s_waitcnt vmcnt(0)
	v_mul_hi_u32 v1, v3, v1
	v_mul_lo_u32 v4, v1, v2
	v_sub_u32_e32 v4, v3, v4
	v_add_u32_e32 v5, 1, v1
	v_cmp_ge_u32_e32 vcc, v4, v2
	v_add_u32_e32 v3, 1, v3
	s_nop 0
	v_cndmask_b32_e32 v1, v1, v5, vcc
	v_sub_u32_e32 v5, v4, v2
	v_cndmask_b32_e32 v4, v4, v5, vcc
	v_add_u32_e32 v5, 1, v1
	v_cmp_ge_u32_e32 vcc, v4, v2
	s_nop 1
	v_cndmask_b32_e32 v1, v1, v5, vcc
	v_mul_lo_u32 v4, v2, v1
	v_add_u32_e32 v2, v4, v2
	v_cmp_ne_u32_e32 vcc, v3, v2
	s_and_saveexec_b64 s[2:3], vcc
	s_xor_b64 s[8:9], exec, s[2:3]
	s_cbranch_execz .LBB0_599
	buffer_inv sc1
	v_readlane_b32 s2, v252, 49
	v_readlane_b32 s3, v252, 50
	s_waitcnt lgkmcnt(0)
	s_nop 3
	global_load_dword v0, v197, s[2:3] sc1
	s_waitcnt vmcnt(0)
	v_cmp_eq_u32_e32 vcc, v0, v1
	s_and_saveexec_b64 s[12:13], vcc
	s_cbranch_execz .LBB0_598
	s_mov_b32 s1, 1
	s_mov_b64 s[18:19], 0
	s_branch .LBB0_589

.LBB0_598:
	s_or_b64 exec, exec, s[12:13]
	s_waitcnt vmcnt(0)
	s_waitcnt vmcnt(0)

.LBB0_639:
	v_readlane_b32 s2, v252, 47
	v_readlane_b32 s3, v252, 48
	v_cvt_f32_u32_e32 v1, v2
	v_sub_u32_e32 v4, 0, v2
	v_rcp_iflag_f32_e32 v1, v1
	s_nop 1
	global_atomic_add v3, v197, v223, s[2:3] sc0
	v_mul_f32_e32 v1, 0x4f7ffffe, v1
	v_cvt_u32_f32_e32 v1, v1
	v_mul_lo_u32 v4, v4, v1
	v_mul_hi_u32 v4, v1, v4
	v_add_u32_e32 v1, v1, v4
	s_waitcnt vmcnt(0)
	v_mul_hi_u32 v1, v3, v1
	v_mul_lo_u32 v4, v1, v2
	v_sub_u32_e32 v4, v3, v4
	v_add_u32_e32 v5, 1, v1
	v_cmp_ge_u32_e32 vcc, v4, v2
	v_add_u32_e32 v3, 1, v3
	s_nop 0
	v_cndmask_b32_e32 v1, v1, v5, vcc
	v_sub_u32_e32 v5, v4, v2
	v_cndmask_b32_e32 v4, v4, v5, vcc
	v_add_u32_e32 v5, 1, v1
	v_cmp_ge_u32_e32 vcc, v4, v2
	s_nop 1
	v_cndmask_b32_e32 v1, v1, v5, vcc
	v_mul_lo_u32 v4, v2, v1
	v_add_u32_e32 v2, v4, v2
	v_cmp_ne_u32_e32 vcc, v3, v2
	s_and_saveexec_b64 s[2:3], vcc
	s_xor_b64 s[8:9], exec, s[2:3]
	s_cbranch_execz .LBB0_653
	buffer_inv sc1
	v_readlane_b32 s2, v252, 49
	v_readlane_b32 s3, v252, 50
	s_waitcnt lgkmcnt(0)
	s_nop 3
	global_load_dword v0, v197, s[2:3] sc1
	s_waitcnt vmcnt(0)
	v_cmp_eq_u32_e32 vcc, v0, v1
	s_and_saveexec_b64 s[12:13], vcc
	s_cbranch_execz .LBB0_652
	s_mov_b32 s26, s30
	s_mov_b32 s1, 1
	s_mov_b64 s[18:19], 0
	s_branch .LBB0_643

.LBB0_895:
	v_readlane_b32 s2, v252, 47
	v_readlane_b32 s3, v252, 48
	v_cvt_f32_u32_e32 v1, v2
	v_sub_u32_e32 v4, 0, v2
	v_rcp_iflag_f32_e32 v1, v1
	s_nop 1
	global_atomic_add v3, v197, v223, s[2:3] sc0
	v_mul_f32_e32 v1, 0x4f7ffffe, v1
	v_cvt_u32_f32_e32 v1, v1
	v_mul_lo_u32 v4, v4, v1
	v_mul_hi_u32 v4, v1, v4
	v_add_u32_e32 v1, v1, v4
	s_waitcnt vmcnt(0)
	v_mul_hi_u32 v1, v3, v1
	v_mul_lo_u32 v4, v1, v2
	v_sub_u32_e32 v4, v3, v4
	v_add_u32_e32 v5, 1, v1
	v_cmp_ge_u32_e32 vcc, v4, v2
	v_add_u32_e32 v3, 1, v3
	s_nop 0
	v_cndmask_b32_e32 v1, v1, v5, vcc
	v_sub_u32_e32 v5, v4, v2
	v_cndmask_b32_e32 v4, v4, v5, vcc
	v_add_u32_e32 v5, 1, v1
	v_cmp_ge_u32_e32 vcc, v4, v2
	s_nop 1
	v_cndmask_b32_e32 v1, v1, v5, vcc
	v_mul_lo_u32 v4, v2, v1
	v_add_u32_e32 v2, v4, v2
	v_cmp_ne_u32_e32 vcc, v3, v2
	s_and_saveexec_b64 s[2:3], vcc
	s_xor_b64 s[8:9], exec, s[2:3]
	s_cbranch_execz .LBB0_909
	buffer_inv sc1
	v_readlane_b32 s2, v252, 49
	v_readlane_b32 s3, v252, 50
	s_waitcnt lgkmcnt(0)
	s_nop 3
	global_load_dword v0, v197, s[2:3] sc1
	s_waitcnt vmcnt(0)
	v_cmp_eq_u32_e32 vcc, v0, v1
	s_and_saveexec_b64 s[12:13], vcc
	s_cbranch_execz .LBB0_908
	s_mov_b32 s26, s30
	s_mov_b32 s2, 1
	s_mov_b64 s[18:19], 0
	s_branch .LBB0_899
